# baseline (speedup 1.0000x reference)
.Lbar_nobc:
.LBB0_62:
	s_or_b64 exec, exec, s[4:5]
	s_mov_b64 s[4:5], exec
	v_mbcnt_lo_u32_b32 v1, s4, 0
	v_mbcnt_hi_u32_b32 v1, s5, v1
	v_cmp_eq_u32_e32 vcc, 0, v1
	s_and_b64 s[30:31], s[28:29], exec
	s_cbranch_scc1 .Lbar_skipw
	s_waitcnt vmcnt(0)
.Lbar_skipw:
	buffer_inv sc1
	s_and_saveexec_b64 s[6:7], vcc
	s_cbranch_execz .LBB0_64
	s_add_i32 s74, s26, 0x900
	s_lshl_b64 s[8:9], s[74:75], 2
	s_add_u32 s8, s24, s8
	s_addc_u32 s9, s25, s9
	s_bcnt1_i32_b64 s4, s[4:5]
	v_mov_b32_e32 v1, s4
